# modulation bias load hoisted to the start of the GEMV item (was a dependent round trip after the reduce barrier)
# speedup vs baseline: 1.0020x; 1.0003x over previous
; __device__ __forceinline__ float siluf(float x) { return x * sigmf(x); }
; __device__ __forceinline__ void prologue_phase(const Args& a, LAS unsigned char* lds, int G) {
;     ...
;         for (int it = blockIdx.x; it < 192; it += G) {
;             const int half = it / 96, r = it % 96, l = r / 48, cgp = r % 48, col = cgp * 64 + lane, kb = half * 512 + wave * 64;
;             const float* wp = ada_w + (size_t)l * D * 3072 + (size_t)kb * 3072 + col;
;             float wv[64];
; #pragma unroll
;             for (int k = 0; k < 64; ++k) wv[k] = wp[(size_t)k * 3072];
;             float a0 = 0.f, a1 = 0.f;
; #pragma unroll
;             for (int k = 0; k < 64; ++k) { const float c0 = cvec[kb + k], c1 = cvec[D + kb + k]; a0 += siluf(c0) * wv[k]; a1 += siluf(c1) * wv[k]; }
.LBB0_23:
	s_mul_hi_i32 s4, s93, 0x2aaaaaab
	s_lshr_b32 s5, s4, 31
	s_ashr_i32 s4, s4, 4
	s_add_i32 s95, s4, s5
	s_mul_i32 s4, s95, 0xffffffa0
	s_add_i32 s4, s93, s4
	s_mul_i32 s5, s4, 43
	s_sext_i32_i16 s94, s5
	s_ashr_i32 s94, s94, 11
	s_bfe_u32 s5, s5, 0x1000f
	s_add_i32 s5, s94, s5
	s_mul_i32 s94, s5, 48
	s_sub_i32 s96, s4, s94
	s_sext_i32_i16 s94, s5
	s_mul_i32 s4, s94, 0x300000
	s_ashr_i32 s5, s4, 31
	s_lshl_b64 s[4:5], s[4:5], 2
	s_add_u32 s4, s74, s4
	s_addc_u32 s5, s75, s5
	v_mov_b64_e32 v[0:1], s[4:5]
	s_sext_i32_i8 s4, s96
	v_lshl_or_b32 v36, s4, 6, v130
	v_lshl_add_u32 v16, s95, 9, v132
	v_mad_i64_i32 v[0:1], s[4:5], v16, s24, v[0:1]
	v_ashrrev_i32_e32 v37, 31, v36
	v_lshl_add_u64 v[0:1], v[36:37], 2, v[0:1]
	v_mov_b32_e32 v62, 0
	s_add_i32 s98, s93, 0x5f
	s_cmpk_gt_u32 s98, 0xbe
	s_cbranch_scc1 .Lmod_nob
	s_mul_i32 s98, s94, 0xc00
	v_add_u32_e32 v62, s98, v36
	v_ashrrev_i32_e32 v63, 31, v62
	v_lshl_add_u64 v[62:63], v[62:63], 2, s[76:77]
	global_load_dword v62, v[62:63], off
.Lmod_nob:
	v_add_lshl_u32 v8, v16, v130, 2
	v_add_u32_e32 v9, 0x1000, v8
	global_load_dword v60, v8, s[70:71]
	global_load_dword v61, v9, s[70:71]
	s_mov_b64 s[98:99], 0x3000
	v_mov_b32_e32 v44, 0
	v_mov_b32_e32 v46, 0
	global_load_dword v64, v[0:1], off
	v_lshl_add_u64 v[6:7], v[0:1], 0, s[98:99]
	global_load_dword v65, v[6:7], off
	v_lshl_add_u64 v[6:7], v[6:7], 0, s[98:99]
	global_load_dword v66, v[6:7], off
	v_lshl_add_u64 v[6:7], v[6:7], 0, s[98:99]
	global_load_dword v67, v[6:7], off
	v_lshl_add_u64 v[6:7], v[6:7], 0, s[98:99]
	global_load_dword v68, v[6:7], off
	v_lshl_add_u64 v[6:7], v[6:7], 0, s[98:99]
	global_load_dword v69, v[6:7], off
	v_lshl_add_u64 v[6:7], v[6:7], 0, s[98:99]
	global_load_dword v70, v[6:7], off
	v_lshl_add_u64 v[6:7], v[6:7], 0, s[98:99]
	global_load_dword v71, v[6:7], off
	v_lshl_add_u64 v[6:7], v[6:7], 0, s[98:99]
	global_load_dword v72, v[6:7], off
	v_lshl_add_u64 v[6:7], v[6:7], 0, s[98:99]
	global_load_dword v73, v[6:7], off
	v_lshl_add_u64 v[6:7], v[6:7], 0, s[98:99]
	global_load_dword v74, v[6:7], off
	v_lshl_add_u64 v[6:7], v[6:7], 0, s[98:99]
	global_load_dword v75, v[6:7], off
	v_lshl_add_u64 v[6:7], v[6:7], 0, s[98:99]
	global_load_dword v76, v[6:7], off
	v_lshl_add_u64 v[6:7], v[6:7], 0, s[98:99]
	global_load_dword v77, v[6:7], off
	v_lshl_add_u64 v[6:7], v[6:7], 0, s[98:99]
	global_load_dword v78, v[6:7], off
	v_lshl_add_u64 v[6:7], v[6:7], 0, s[98:99]
	global_load_dword v79, v[6:7], off
	v_lshl_add_u64 v[6:7], v[6:7], 0, s[98:99]
	global_load_dword v80, v[6:7], off
	v_lshl_add_u64 v[6:7], v[6:7], 0, s[98:99]
	global_load_dword v81, v[6:7], off
	v_lshl_add_u64 v[6:7], v[6:7], 0, s[98:99]
	global_load_dword v82, v[6:7], off
	v_lshl_add_u64 v[6:7], v[6:7], 0, s[98:99]
	global_load_dword v83, v[6:7], off
	v_lshl_add_u64 v[6:7], v[6:7], 0, s[98:99]
	global_load_dword v84, v[6:7], off
	v_lshl_add_u64 v[6:7], v[6:7], 0, s[98:99]
	global_load_dword v85, v[6:7], off
	v_lshl_add_u64 v[6:7], v[6:7], 0, s[98:99]
	global_load_dword v86, v[6:7], off
	v_lshl_add_u64 v[6:7], v[6:7], 0, s[98:99]
	global_load_dword v87, v[6:7], off
	v_lshl_add_u64 v[6:7], v[6:7], 0, s[98:99]
	global_load_dword v88, v[6:7], off
	v_lshl_add_u64 v[6:7], v[6:7], 0, s[98:99]
	global_load_dword v89, v[6:7], off
	v_lshl_add_u64 v[6:7], v[6:7], 0, s[98:99]
	global_load_dword v90, v[6:7], off
	v_lshl_add_u64 v[6:7], v[6:7], 0, s[98:99]
	global_load_dword v91, v[6:7], off
	v_lshl_add_u64 v[6:7], v[6:7], 0, s[98:99]
	global_load_dword v92, v[6:7], off
	v_lshl_add_u64 v[6:7], v[6:7], 0, s[98:99]
	global_load_dword v93, v[6:7], off
	v_lshl_add_u64 v[6:7], v[6:7], 0, s[98:99]
	global_load_dword v94, v[6:7], off
	v_lshl_add_u64 v[6:7], v[6:7], 0, s[98:99]
	global_load_dword v95, v[6:7], off
	v_lshl_add_u64 v[6:7], v[6:7], 0, s[98:99]
	global_load_dword v96, v[6:7], off
	v_lshl_add_u64 v[6:7], v[6:7], 0, s[98:99]
	global_load_dword v97, v[6:7], off
	v_lshl_add_u64 v[6:7], v[6:7], 0, s[98:99]
	global_load_dword v98, v[6:7], off
	v_lshl_add_u64 v[6:7], v[6:7], 0, s[98:99]
	global_load_dword v99, v[6:7], off
	v_lshl_add_u64 v[6:7], v[6:7], 0, s[98:99]
	global_load_dword v100, v[6:7], off
	v_lshl_add_u64 v[6:7], v[6:7], 0, s[98:99]
	global_load_dword v101, v[6:7], off
	v_lshl_add_u64 v[6:7], v[6:7], 0, s[98:99]
	global_load_dword v102, v[6:7], off
	v_lshl_add_u64 v[6:7], v[6:7], 0, s[98:99]
	global_load_dword v103, v[6:7], off
	v_lshl_add_u64 v[6:7], v[6:7], 0, s[98:99]
	global_load_dword v104, v[6:7], off
	v_lshl_add_u64 v[6:7], v[6:7], 0, s[98:99]
	global_load_dword v105, v[6:7], off
	v_lshl_add_u64 v[6:7], v[6:7], 0, s[98:99]
	global_load_dword v106, v[6:7], off
	v_lshl_add_u64 v[6:7], v[6:7], 0, s[98:99]
	global_load_dword v107, v[6:7], off
	v_lshl_add_u64 v[6:7], v[6:7], 0, s[98:99]
	s_waitcnt vmcnt(44)
; __device__ __forceinline__ float siluf(float x) { return x * sigmf(x); }
; __device__ __forceinline__ void prologue_phase(const Args& a, LAS unsigned char* lds, int G) {
;     ...
;             float wv[64];
; #pragma unroll
;             for (int k = 0; k < 64; ++k) wv[k] = wp[(size_t)k * 3072];
;             float a0 = 0.f, a1 = 0.f;
; #pragma unroll
;             for (int k = 0; k < 64; ++k) { const float c0 = cvec[kb + k], c1 = cvec[D + kb + k]; a0 += siluf(c0) * wv[k]; a1 += siluf(c1) * wv[k]; }
	v_mul_f32_e32 v10, 0xbfb8aa3b, v60
	v_mul_f32_e32 v11, 0xbfb8aa3b, v61
	v_exp_f32_e32 v10, v10
	v_exp_f32_e32 v11, v11
	s_nop 0
	v_add_f32_e32 v10, 1.0, v10
	v_add_f32_e32 v11, 1.0, v11
	v_rcp_f32_e32 v10, v10
	v_rcp_f32_e32 v11, v11
	s_nop 0
	v_mul_f32_e32 v60, v60, v10
	v_mul_f32_e32 v61, v61, v11
	global_load_dword v108, v[6:7], off
	v_lshl_add_u64 v[6:7], v[6:7], 0, s[98:99]
	global_load_dword v109, v[6:7], off
	v_lshl_add_u64 v[6:7], v[6:7], 0, s[98:99]
	global_load_dword v110, v[6:7], off
	v_lshl_add_u64 v[6:7], v[6:7], 0, s[98:99]
	global_load_dword v111, v[6:7], off
	v_lshl_add_u64 v[6:7], v[6:7], 0, s[98:99]
	global_load_dword v112, v[6:7], off
	v_lshl_add_u64 v[6:7], v[6:7], 0, s[98:99]
	global_load_dword v113, v[6:7], off
	v_lshl_add_u64 v[6:7], v[6:7], 0, s[98:99]
	global_load_dword v114, v[6:7], off
	v_lshl_add_u64 v[6:7], v[6:7], 0, s[98:99]
	global_load_dword v115, v[6:7], off
	v_lshl_add_u64 v[6:7], v[6:7], 0, s[98:99]
	global_load_dword v116, v[6:7], off
	v_lshl_add_u64 v[6:7], v[6:7], 0, s[98:99]
	global_load_dword v117, v[6:7], off
	v_lshl_add_u64 v[6:7], v[6:7], 0, s[98:99]
	global_load_dword v118, v[6:7], off
	v_lshl_add_u64 v[6:7], v[6:7], 0, s[98:99]
	global_load_dword v119, v[6:7], off
	v_lshl_add_u64 v[6:7], v[6:7], 0, s[98:99]
	global_load_dword v120, v[6:7], off
	v_lshl_add_u64 v[6:7], v[6:7], 0, s[98:99]
	global_load_dword v121, v[6:7], off
	v_lshl_add_u64 v[6:7], v[6:7], 0, s[98:99]
	global_load_dword v122, v[6:7], off
	v_lshl_add_u64 v[6:7], v[6:7], 0, s[98:99]
	global_load_dword v123, v[6:7], off
	v_lshl_add_u64 v[6:7], v[6:7], 0, s[98:99]
	global_load_dword v124, v[6:7], off
	v_lshl_add_u64 v[6:7], v[6:7], 0, s[98:99]
	global_load_dword v125, v[6:7], off
	v_lshl_add_u64 v[6:7], v[6:7], 0, s[98:99]
	global_load_dword v126, v[6:7], off
	v_lshl_add_u64 v[6:7], v[6:7], 0, s[98:99]
	global_load_dword v127, v[6:7], off
	v_readlane_b32 s4, v60, 0
	v_readlane_b32 s5, v61, 0
	v_readlane_b32 s98, v60, 1
	v_readlane_b32 s99, v61, 1
	v_readlane_b32 s100, v60, 2
	v_readlane_b32 s101, v61, 2
	s_waitcnt vmcnt(48)
	v_fmac_f32_e32 v44, s4, v64
	v_fmac_f32_e32 v46, s5, v64
	v_readlane_b32 s4, v60, 3
	v_readlane_b32 s5, v61, 3
	v_fmac_f32_e32 v44, s98, v65
	v_fmac_f32_e32 v46, s99, v65
	v_readlane_b32 s98, v60, 4
	v_readlane_b32 s99, v61, 4
	v_fmac_f32_e32 v44, s100, v66
	v_fmac_f32_e32 v46, s101, v66
	v_readlane_b32 s100, v60, 5
	v_readlane_b32 s101, v61, 5
	v_fmac_f32_e32 v44, s4, v67
	v_fmac_f32_e32 v46, s5, v67
	v_readlane_b32 s4, v60, 6
	v_readlane_b32 s5, v61, 6
	v_fmac_f32_e32 v44, s98, v68
	v_fmac_f32_e32 v46, s99, v68
	v_readlane_b32 s98, v60, 7
	v_readlane_b32 s99, v61, 7
	v_fmac_f32_e32 v44, s100, v69
	v_fmac_f32_e32 v46, s101, v69
	v_readlane_b32 s100, v60, 8
	v_readlane_b32 s101, v61, 8
	v_fmac_f32_e32 v44, s4, v70
	v_fmac_f32_e32 v46, s5, v70
	v_readlane_b32 s4, v60, 9
	v_readlane_b32 s5, v61, 9
	v_fmac_f32_e32 v44, s98, v71
	v_fmac_f32_e32 v46, s99, v71
	v_readlane_b32 s98, v60, 10
	v_readlane_b32 s99, v61, 10
	v_fmac_f32_e32 v44, s100, v72
	v_fmac_f32_e32 v46, s101, v72
	v_readlane_b32 s100, v60, 11
	v_readlane_b32 s101, v61, 11
	v_fmac_f32_e32 v44, s4, v73
	v_fmac_f32_e32 v46, s5, v73
	v_readlane_b32 s4, v60, 12
	v_readlane_b32 s5, v61, 12
	v_fmac_f32_e32 v44, s98, v74
	v_fmac_f32_e32 v46, s99, v74
	v_readlane_b32 s98, v60, 13
	v_readlane_b32 s99, v61, 13
	v_fmac_f32_e32 v44, s100, v75
	v_fmac_f32_e32 v46, s101, v75
	v_readlane_b32 s100, v60, 14
	v_readlane_b32 s101, v61, 14
	v_fmac_f32_e32 v44, s4, v76
	v_fmac_f32_e32 v46, s5, v76
	v_readlane_b32 s4, v60, 15
	v_readlane_b32 s5, v61, 15
	v_fmac_f32_e32 v44, s98, v77
	v_fmac_f32_e32 v46, s99, v77
	v_readlane_b32 s98, v60, 16
	v_readlane_b32 s99, v61, 16
	v_fmac_f32_e32 v44, s100, v78
	v_fmac_f32_e32 v46, s101, v78
	v_readlane_b32 s100, v60, 17
	v_readlane_b32 s101, v61, 17
	v_fmac_f32_e32 v44, s4, v79
	v_fmac_f32_e32 v46, s5, v79
	v_readlane_b32 s4, v60, 18
	v_readlane_b32 s5, v61, 18
	s_waitcnt vmcnt(32)
; __device__ __forceinline__ float siluf(float x) { return x * sigmf(x); }
; __device__ __forceinline__ void prologue_phase(const Args& a, LAS unsigned char* lds, int G) {
;     ...
;             for (int k = 0; k < 64; ++k) { const float c0 = cvec[kb + k], c1 = cvec[D + kb + k]; a0 += siluf(c0) * wv[k]; a1 += siluf(c1) * wv[k]; }
;             red[(wave * 2 + 0) * 64 + lane] = a0; red[(wave * 2 + 1) * 64 + lane] = a1;
;             __syncthreads();
;             if (wave < 2) { float s = half == 0 ? ada_b[l * 3072 + col] : 0.f;
; #pragma unroll
;                 for (int w = 0; w < 8; ++w) s += red[(w * 2 + wave) * 64 + lane];
;                 atomicAdd(mod + (l * 2 + wave) * 3072 + col, s); }
	v_fmac_f32_e32 v44, s98, v80
	v_fmac_f32_e32 v46, s99, v80
	v_readlane_b32 s98, v60, 19
	v_readlane_b32 s99, v61, 19
	v_fmac_f32_e32 v44, s100, v81
	v_fmac_f32_e32 v46, s101, v81
	v_readlane_b32 s100, v60, 20
	v_readlane_b32 s101, v61, 20
	v_fmac_f32_e32 v44, s4, v82
	v_fmac_f32_e32 v46, s5, v82
	v_readlane_b32 s4, v60, 21
	v_readlane_b32 s5, v61, 21
	v_fmac_f32_e32 v44, s98, v83
	v_fmac_f32_e32 v46, s99, v83
	v_readlane_b32 s98, v60, 22
	v_readlane_b32 s99, v61, 22
	v_fmac_f32_e32 v44, s100, v84
	v_fmac_f32_e32 v46, s101, v84
	v_readlane_b32 s100, v60, 23
	v_readlane_b32 s101, v61, 23
	v_fmac_f32_e32 v44, s4, v85
	v_fmac_f32_e32 v46, s5, v85
	v_readlane_b32 s4, v60, 24
	v_readlane_b32 s5, v61, 24
	v_fmac_f32_e32 v44, s98, v86
	v_fmac_f32_e32 v46, s99, v86
	v_readlane_b32 s98, v60, 25
	v_readlane_b32 s99, v61, 25
	v_fmac_f32_e32 v44, s100, v87
	v_fmac_f32_e32 v46, s101, v87
	v_readlane_b32 s100, v60, 26
	v_readlane_b32 s101, v61, 26
	v_fmac_f32_e32 v44, s4, v88
	v_fmac_f32_e32 v46, s5, v88
	v_readlane_b32 s4, v60, 27
	v_readlane_b32 s5, v61, 27
	v_fmac_f32_e32 v44, s98, v89
	v_fmac_f32_e32 v46, s99, v89
	v_readlane_b32 s98, v60, 28
	v_readlane_b32 s99, v61, 28
	v_fmac_f32_e32 v44, s100, v90
	v_fmac_f32_e32 v46, s101, v90
	v_readlane_b32 s100, v60, 29
	v_readlane_b32 s101, v61, 29
	v_fmac_f32_e32 v44, s4, v91
	v_fmac_f32_e32 v46, s5, v91
	v_readlane_b32 s4, v60, 30
	v_readlane_b32 s5, v61, 30
	v_fmac_f32_e32 v44, s98, v92
	v_fmac_f32_e32 v46, s99, v92
	v_readlane_b32 s98, v60, 31
	v_readlane_b32 s99, v61, 31
	v_fmac_f32_e32 v44, s100, v93
	v_fmac_f32_e32 v46, s101, v93
	v_readlane_b32 s100, v60, 32
	v_readlane_b32 s101, v61, 32
	v_fmac_f32_e32 v44, s4, v94
	v_fmac_f32_e32 v46, s5, v94
	v_readlane_b32 s4, v60, 33
	v_readlane_b32 s5, v61, 33
	v_fmac_f32_e32 v44, s98, v95
	v_fmac_f32_e32 v46, s99, v95
	v_readlane_b32 s98, v60, 34
	v_readlane_b32 s99, v61, 34
	s_waitcnt vmcnt(16)
	v_fmac_f32_e32 v44, s100, v96
	v_fmac_f32_e32 v46, s101, v96
	v_readlane_b32 s100, v60, 35
	v_readlane_b32 s101, v61, 35
	v_fmac_f32_e32 v44, s4, v97
	v_fmac_f32_e32 v46, s5, v97
	v_readlane_b32 s4, v60, 36
	v_readlane_b32 s5, v61, 36
	v_fmac_f32_e32 v44, s98, v98
	v_fmac_f32_e32 v46, s99, v98
	v_readlane_b32 s98, v60, 37
	v_readlane_b32 s99, v61, 37
	v_fmac_f32_e32 v44, s100, v99
	v_fmac_f32_e32 v46, s101, v99
	v_readlane_b32 s100, v60, 38
	v_readlane_b32 s101, v61, 38
	v_fmac_f32_e32 v44, s4, v100
	v_fmac_f32_e32 v46, s5, v100
	v_readlane_b32 s4, v60, 39
	v_readlane_b32 s5, v61, 39
	v_fmac_f32_e32 v44, s98, v101
	v_fmac_f32_e32 v46, s99, v101
	v_readlane_b32 s98, v60, 40
	v_readlane_b32 s99, v61, 40
	v_fmac_f32_e32 v44, s100, v102
	v_fmac_f32_e32 v46, s101, v102
	v_readlane_b32 s100, v60, 41
	v_readlane_b32 s101, v61, 41
	v_fmac_f32_e32 v44, s4, v103
	v_fmac_f32_e32 v46, s5, v103
	v_readlane_b32 s4, v60, 42
	v_readlane_b32 s5, v61, 42
	v_fmac_f32_e32 v44, s98, v104
	v_fmac_f32_e32 v46, s99, v104
	v_readlane_b32 s98, v60, 43
	v_readlane_b32 s99, v61, 43
	v_fmac_f32_e32 v44, s100, v105
	v_fmac_f32_e32 v46, s101, v105
	v_readlane_b32 s100, v60, 44
	v_readlane_b32 s101, v61, 44
	v_fmac_f32_e32 v44, s4, v106
	v_fmac_f32_e32 v46, s5, v106
	v_readlane_b32 s4, v60, 45
	v_readlane_b32 s5, v61, 45
	v_fmac_f32_e32 v44, s98, v107
	v_fmac_f32_e32 v46, s99, v107
	v_readlane_b32 s98, v60, 46
	v_readlane_b32 s99, v61, 46
	v_fmac_f32_e32 v44, s100, v108
	v_fmac_f32_e32 v46, s101, v108
	v_readlane_b32 s100, v60, 47
	v_readlane_b32 s101, v61, 47
	v_fmac_f32_e32 v44, s4, v109
	v_fmac_f32_e32 v46, s5, v109
	v_readlane_b32 s4, v60, 48
	v_readlane_b32 s5, v61, 48
	v_fmac_f32_e32 v44, s98, v110
	v_fmac_f32_e32 v46, s99, v110
	v_readlane_b32 s98, v60, 49
	v_readlane_b32 s99, v61, 49
	v_fmac_f32_e32 v44, s100, v111
	v_fmac_f32_e32 v46, s101, v111
	v_readlane_b32 s100, v60, 50
	v_readlane_b32 s101, v61, 50
	s_waitcnt vmcnt(0)
	v_fmac_f32_e32 v44, s4, v112
	v_fmac_f32_e32 v46, s5, v112
	v_readlane_b32 s4, v60, 51
	v_readlane_b32 s5, v61, 51
	v_fmac_f32_e32 v44, s98, v113
	v_fmac_f32_e32 v46, s99, v113
	v_readlane_b32 s98, v60, 52
	v_readlane_b32 s99, v61, 52
	v_fmac_f32_e32 v44, s100, v114
	v_fmac_f32_e32 v46, s101, v114
	v_readlane_b32 s100, v60, 53
	v_readlane_b32 s101, v61, 53
	v_fmac_f32_e32 v44, s4, v115
	v_fmac_f32_e32 v46, s5, v115
	v_readlane_b32 s4, v60, 54
	v_readlane_b32 s5, v61, 54
	v_fmac_f32_e32 v44, s98, v116
	v_fmac_f32_e32 v46, s99, v116
	v_readlane_b32 s98, v60, 55
	v_readlane_b32 s99, v61, 55
	v_fmac_f32_e32 v44, s100, v117
	v_fmac_f32_e32 v46, s101, v117
	v_readlane_b32 s100, v60, 56
	v_readlane_b32 s101, v61, 56
	v_fmac_f32_e32 v44, s4, v118
	v_fmac_f32_e32 v46, s5, v118
	v_readlane_b32 s4, v60, 57
	v_readlane_b32 s5, v61, 57
	v_fmac_f32_e32 v44, s98, v119
	v_fmac_f32_e32 v46, s99, v119
	v_readlane_b32 s98, v60, 58
	v_readlane_b32 s99, v61, 58
	v_fmac_f32_e32 v44, s100, v120
	v_fmac_f32_e32 v46, s101, v120
	v_readlane_b32 s100, v60, 59
	v_readlane_b32 s101, v61, 59
	v_fmac_f32_e32 v44, s4, v121
	v_fmac_f32_e32 v46, s5, v121
	v_readlane_b32 s4, v60, 60
	v_readlane_b32 s5, v61, 60
	v_fmac_f32_e32 v44, s98, v122
	v_fmac_f32_e32 v46, s99, v122
	v_readlane_b32 s98, v60, 61
	v_readlane_b32 s99, v61, 61
	v_fmac_f32_e32 v44, s100, v123
	v_fmac_f32_e32 v46, s101, v123
	v_readlane_b32 s100, v60, 62
	v_readlane_b32 s101, v61, 62
	v_fmac_f32_e32 v44, s4, v124
	v_fmac_f32_e32 v46, s5, v124
	v_readlane_b32 s4, v60, 63
	v_readlane_b32 s5, v61, 63
	v_fmac_f32_e32 v44, s98, v125
	v_fmac_f32_e32 v46, s99, v125
	v_fmac_f32_e32 v44, s100, v126
	v_fmac_f32_e32 v46, s101, v126
	v_fmac_f32_e32 v44, s4, v127
	v_fmac_f32_e32 v46, s5, v127
	ds_write2st64_b32 v134, v44, v46 offset1:1
	s_waitcnt lgkmcnt(0)
	s_barrier
	s_and_saveexec_b64 s[4:5], vcc
	s_cbranch_execz .LBB0_22
	s_add_i32 s95, s93, 0x5f
	s_cmpk_gt_u32 s95, 0xbe
	v_mov_b32_e32 v0, 0
	s_cbranch_scc1 .LBB0_21
	v_mov_b32_e32 v0, v62
	s_branch .LBB0_21
